# down GEMM decode-row exchange: the 8 partner slots polled together as well
# baseline (speedup 1.0000x reference)
.LBB0_1227:
	s_or_b64 exec, exec, s[16:17]
	v_lshl_add_u64 v[22:23], s[14:15], 0, v[10:11]
	v_lshlrev_b32_e32 v24, 3, v8
	v_mov_b32_e32 v25, v11
	v_lshl_add_u64 v[22:23], v[22:23], 0, v[24:25]
	s_waitcnt lgkmcnt(0)
	s_waitcnt lgkmcnt(0)
	s_mov_b32 s16, 0
.Lxch8_dn_poll:
	global_load_dwordx4 v[200:203], v[22:23], off sc1
	global_load_dwordx4 v[204:207], v[22:23], off offset:16 sc1
	global_load_dwordx4 v[208:211], v[22:23], off offset:32 sc1
	global_load_dwordx4 v[212:215], v[22:23], off offset:48 sc1
	s_waitcnt vmcnt(0)
	v_min3_u32 v216, v201, v203, v205
	v_min3_u32 v216, v216, v207, v209
	v_min3_u32 v216, v216, v211, v213
	v_min_u32_e32 v216, v216, v215
	v_cmp_eq_u32_e32 vcc, 0, v216
	s_cbranch_vccz .Lxch8_dn_ready
	s_add_i32 s16, s16, 1
	s_cmp_lt_u32 s16, 0x400000
	s_cbranch_scc0 .Lxch8_dn_ready
	s_sleep 1
	s_branch .Lxch8_dn_poll
.Lxch8_dn_ready:
	v_mov_b32_e32 v19, v200
	v_mov_b32_e32 v20, v202
	v_mov_b32_e32 v31, v204
	v_mov_b32_e32 v32, v206
	v_mov_b32_e32 v33, v208
	v_mov_b32_e32 v34, v210
	v_mov_b32_e32 v35, v212
	v_mov_b32_e32 v36, v214
	s_mov_b64 s[14:15], exec
	s_branch .LBB0_1220
